# sc1_p7_stores_plus_copies
# baseline (speedup 1.0000x reference)
; __device__ __forceinline__ unsigned pk2(float lo, float hi) { f32x2v v = {lo, hi}; b16x2v b = __builtin_convertvector(v, b16x2v); return __builtin_bit_cast(unsigned, b); }
;     __device__ __forceinline__ bf16_t* O() const { return (bf16_t*)(ws + WS_O); }
;     __device__ __forceinline__ void operator()(const f32x4 (&acc)[2][2][4][2], const Unit& u, int wr, int wc, int fr, int fq) const {
;         const int colb = u.pn * 256 + 32 * wc + 8 * fq;
;         f32x4 c1v[2][2], c2v[2][2];
; #pragma unroll
;         for (int bj = 0; bj < 2; ++bj)
; #pragma unroll
;             for (int n = 0; n < 2; ++n) { const int col = colb + 128 * bj + 4 * n; c1v[bj][n] = *(const f32x4*)(c1 + col); c2v[bj][n] = *(const f32x4*)(c2 + col);
;                 if (HAS_BIAS) c2v[bj][n] = c2v[bj][n] + *(const f32x4*)(bias + col); }
; #pragma unroll
;         for (int ai = 0; ai < 2; ++ai)
; #pragma unroll
;             for (int m = 0; m < 4; ++m) {
;                 const int row = u.pm * 256 + ai * 128 + wr * 64 + m * 16 + fr;
;                 const f32x2v s2 = *(const f32x2v*)(stp + 2 * row); const float mu = s2.x * (1.0f / DM); const float rs = rsqrtf(fmaxf(s2.y * (1.0f / DM) - mu * mu, 0.f) + LN_EPS);
; #pragma unroll
;                 for (int bj = 0; bj < 2; ++bj) {
;                     f32x4 v0 = (acc[ai][bj][m][0] - c1v[bj][0] * mu) * rs + c2v[bj][0], v1 = (acc[ai][bj][m][1] - c1v[bj][1] * mu) * rs + c2v[bj][1];
;                     if (ACT == 1) {
; #pragma unroll
;                         for (int e = 0; e < 4; ++e) { const float a = fmaxf(v0[e], 0.f), c = fmaxf(v1[e], 0.f); v0[e] = a * a; v1[e] = c * c; }
;                     }
;                     v0 = v0 * scale; v1 = v1 * scale;
;                     u32x4 w; w.x = pk2(v0[0], v0[1]); w.y = pk2(v0[2], v0[3]); w.z = pk2(v1[0], v1[1]); w.w = pk2(v1[2], v1[3]);
;                     *(u32x4*)(O + (size_t)row * ldc + colb + 128 * bj) = w;
;                 }
;             }
;     }
.LBB0_1123:
	v_lshl_or_b32 v160, s1, 8, v187
	v_lshl_add_u32 v178, s0, 8, v185
	v_ashrrev_i32_e32 v161, 31, v160
	v_lshlrev_b32_e32 v92, 1, v178
	v_lshlrev_b64 v[88:89], 2, v[160:161]
	v_ashrrev_i32_e32 v93, 31, v92
	v_lshl_add_u64 v[84:85], s[8:9], 0, v[88:89]
	v_lshl_add_u64 v[90:91], s[10:11], 0, v[88:89]
	v_lshl_add_u64 v[88:89], s[46:47], 0, v[88:89]
	v_lshl_add_u64 v[92:93], v[92:93], 2, s[6:7]
	global_load_dwordx4 v[80:83], v[84:85], off offset:16
	s_nop 0
	global_load_dwordx4 v[84:87], v[84:85], off
	s_nop 0
	global_load_dwordx4 v[166:169], v[90:91], off offset:16
	global_load_dwordx4 v[162:165], v[90:91], off
	global_load_dwordx4 v[174:177], v[88:89], off offset:16
	global_load_dwordx4 v[194:197], v[88:89], off
	global_load_dwordx2 v[170:171], v[92:93], off
	v_or_b32_e32 v90, 0x80, v160
	v_ashrrev_i32_e32 v91, 31, v90
	v_lshlrev_b64 v[90:91], 2, v[90:91]
	v_lshl_add_u64 v[92:93], s[10:11], 0, v[90:91]
	global_load_dwordx4 v[198:201], v[92:93], off
	global_load_dwordx4 v[202:205], v[88:89], off offset:512
	global_load_dwordx4 v[206:209], v[88:89], off offset:528
	global_load_dwordx4 v[210:213], v[92:93], off offset:16
	v_lshl_add_u64 v[88:89], s[8:9], 0, v[90:91]
	global_load_dwordx4 v[92:95], v[88:89], off
	v_or_b32_e32 v88, 0x84, v160
	v_ashrrev_i32_e32 v89, 31, v88
	v_lshl_add_u64 v[88:89], v[88:89], 2, s[8:9]
	global_load_dwordx4 v[88:91], v[88:89], off
	v_ashrrev_i32_e32 v179, 31, v178
	v_lshlrev_b64 v[214:215], 13, v[178:179]
	v_lshlrev_b64 v[172:173], 1, v[160:161]
	v_lshl_add_u64 v[160:161], s[4:5], 0, v[214:215]
	v_lshl_add_u64 v[214:215], v[160:161], 0, v[172:173]
	s_waitcnt vmcnt(0)
	v_pk_add_f32 v[166:167], v[166:167], v[174:175]
	v_pk_add_f32 v[162:163], v[162:163], v[194:195]
	v_pk_mul_f32 v[194:195], v[170:171], s[22:23] op_sel_hi:[1,0]
	v_pk_add_f32 v[160:161], v[164:165], v[196:197]
	v_fma_f32 v179, -v194, v194, v195
	v_max_f32_e32 v179, 0, v179
	v_add_f32_e32 v179, 0x3727c5ac, v179
	v_mul_f32_e32 v191, 0x4b800000, v179
	v_cmp_gt_f32_e32 vcc, s63, v179
	v_pk_add_f32 v[164:165], v[168:169], v[176:177]
	v_xor_b32_e32 v177, 0x80000000, v87
	v_cndmask_b32_e32 v179, v179, v191, vcc
	v_rsq_f32_e32 v179, v179
	v_xor_b32_e32 v176, 0x80000000, v86
	v_xor_b32_e32 v175, 0x80000000, v83
	v_xor_b32_e32 v174, 0x80000000, v82
	v_xor_b32_e32 v95, 0x80000000, v95
	v_xor_b32_e32 v94, 0x80000000, v94
	v_xor_b32_e32 v91, 0x80000000, v91
	v_xor_b32_e32 v90, 0x80000000, v90
	v_mul_f32_e32 v191, 0x45800000, v179
	v_pk_fma_f32 v[140:141], v[84:85], v[194:195], v[140:141] op_sel_hi:[1,0,1] neg_lo:[1,0,0] neg_hi:[1,0,0]
	v_pk_fma_f32 v[142:143], v[176:177], v[194:195], v[142:143] op_sel_hi:[1,0,1]
	v_pk_fma_f32 v[136:137], v[80:81], v[194:195], v[136:137] op_sel_hi:[1,0,1] neg_lo:[1,0,0] neg_hi:[1,0,0]
	v_pk_fma_f32 v[138:139], v[174:175], v[194:195], v[138:139] op_sel_hi:[1,0,1]
	v_pk_fma_f32 v[132:133], v[92:93], v[194:195], v[132:133] op_sel_hi:[1,0,1] neg_lo:[1,0,0] neg_hi:[1,0,0]
	v_pk_fma_f32 v[128:129], v[88:89], v[194:195], v[128:129] op_sel_hi:[1,0,1] neg_lo:[1,0,0] neg_hi:[1,0,0]
	v_pk_fma_f32 v[134:135], v[94:95], v[194:195], v[134:135] op_sel_hi:[1,0,1]
	v_pk_fma_f32 v[130:131], v[90:91], v[194:195], v[130:131] op_sel_hi:[1,0,1]
	v_cndmask_b32_e32 v194, v179, v191, vcc
	v_pk_add_f32 v[168:169], v[212:213], v[208:209]
	v_pk_add_f32 v[170:171], v[210:211], v[206:207]
	v_pk_fma_f32 v[142:143], v[142:143], v[194:195], v[160:161] op_sel_hi:[1,0,1]
	v_pk_fma_f32 v[140:141], v[140:141], v[194:195], v[162:163] op_sel_hi:[1,0,1]
	v_pk_fma_f32 v[138:139], v[138:139], v[194:195], v[164:165] op_sel_hi:[1,0,1]
	v_pk_fma_f32 v[136:137], v[136:137], v[194:195], v[166:167] op_sel_hi:[1,0,1]
	v_pk_fma_f32 v[196:197], v[130:131], v[194:195], v[168:169] op_sel_hi:[1,0,1]
	v_pk_fma_f32 v[128:129], v[128:129], v[194:195], v[170:171] op_sel_hi:[1,0,1]
	v_max_f32_e32 v130, 0, v140
	v_max_f32_e32 v136, 0, v136
	v_max_f32_e32 v131, 0, v141
	v_max_f32_e32 v137, 0, v137
	v_max_f32_e32 v140, 0, v142
	v_max_f32_e32 v138, 0, v138
	v_max_f32_e32 v141, 0, v143
	v_max_f32_e32 v139, 0, v139
	v_pk_add_f32 v[82:83], v[200:201], v[204:205]
	v_pk_add_f32 v[86:87], v[198:199], v[202:203]
	v_max_f32_e32 v128, 0, v128
	v_max_f32_e32 v129, 0, v129
	v_pk_mul_f32 v[130:131], v[130:131], v[130:131]
	v_pk_mul_f32 v[136:137], v[136:137], v[136:137]
	v_pk_mul_f32 v[140:141], v[140:141], v[140:141]
	v_pk_mul_f32 v[138:139], v[138:139], v[138:139]
	v_pk_fma_f32 v[134:135], v[134:135], v[194:195], v[82:83] op_sel_hi:[1,0,1]
	v_pk_fma_f32 v[132:133], v[132:133], v[194:195], v[86:87] op_sel_hi:[1,0,1]
	v_pk_mul_f32 v[142:143], v[128:129], v[128:129]
	v_cvt_pk_bf16_f32 v128, v130, v131
	v_cvt_pk_bf16_f32 v129, v140, v141
	v_cvt_pk_bf16_f32 v130, v136, v137
	v_cvt_pk_bf16_f32 v131, v138, v139
	v_max_f32_e32 v132, 0, v132
	v_max_f32_e32 v133, 0, v133
	global_store_dwordx4 v[214:215], v[128:131], off sc1
	v_pk_mul_f32 v[132:133], v[132:133], v[132:133]
	s_nop 0
	v_max_f32_e32 v128, 0, v134
	v_max_f32_e32 v130, 0, v196
	v_max_f32_e32 v129, 0, v135
	v_max_f32_e32 v131, 0, v197
	v_pk_mul_f32 v[134:135], v[128:129], v[128:129]
	v_pk_mul_f32 v[136:137], v[130:131], v[130:131]
	v_cvt_pk_bf16_f32 v128, v132, v133
	v_cvt_pk_bf16_f32 v129, v134, v135
	v_cvt_pk_bf16_f32 v130, v142, v143
	v_cvt_pk_bf16_f32 v131, v136, v137
	global_store_dwordx4 v[214:215], v[128:131], off offset:256 sc1
	v_or_b32_e32 v132, 32, v178
	v_lshlrev_b32_e32 v134, 1, v132
	v_or_b32_e32 v128, 16, v178
	v_lshlrev_b32_e32 v130, 1, v128
	v_ashrrev_i32_e32 v131, 31, v130
	v_lshl_add_u64 v[130:131], v[130:131], 2, s[6:7]
	global_load_dwordx2 v[130:131], v[130:131], off
	v_ashrrev_i32_e32 v129, 31, v128
	v_lshlrev_b64 v[128:129], 13, v[128:129]
	v_lshl_add_u64 v[128:129], s[4:5], 0, v[128:129]
	v_ashrrev_i32_e32 v135, 31, v134
	v_lshl_add_u64 v[128:129], v[128:129], 0, v[172:173]
	v_lshl_add_u64 v[134:135], v[134:135], 2, s[6:7]
	s_waitcnt vmcnt(0)
; __device__ __forceinline__ unsigned pk2(float lo, float hi) { f32x2v v = {lo, hi}; b16x2v b = __builtin_convertvector(v, b16x2v); return __builtin_bit_cast(unsigned, b); }
;     __device__ __forceinline__ bf16_t* O() const { return (bf16_t*)(ws + WS_O); }
;     __device__ __forceinline__ void operator()(const f32x4 (&acc)[2][2][4][2], const Unit& u, int wr, int wc, int fr, int fq) const {
;     ...
;             for (int m = 0; m < 4; ++m) {
;                 const int row = u.pm * 256 + ai * 128 + wr * 64 + m * 16 + fr;
;                 const f32x2v s2 = *(const f32x2v*)(stp + 2 * row); const float mu = s2.x * (1.0f / DM); const float rs = rsqrtf(fmaxf(s2.y * (1.0f / DM) - mu * mu, 0.f) + LN_EPS);
; #pragma unroll
;                 for (int bj = 0; bj < 2; ++bj) {
;                     f32x4 v0 = (acc[ai][bj][m][0] - c1v[bj][0] * mu) * rs + c2v[bj][0], v1 = (acc[ai][bj][m][1] - c1v[bj][1] * mu) * rs + c2v[bj][1];
;                     if (ACT == 1) {
; #pragma unroll
;                         for (int e = 0; e < 4; ++e) { const float a = fmaxf(v0[e], 0.f), c = fmaxf(v1[e], 0.f); v0[e] = a * a; v1[e] = c * c; }
;                     }
;                     v0 = v0 * scale; v1 = v1 * scale;
;                     u32x4 w; w.x = pk2(v0[0], v0[1]); w.y = pk2(v0[2], v0[3]); w.z = pk2(v1[0], v1[1]); w.w = pk2(v1[2], v1[3]);
;                     *(u32x4*)(O + (size_t)row * ldc + colb + 128 * bj) = w;
;                 }
	v_pk_mul_f32 v[130:131], v[130:131], s[22:23] op_sel_hi:[1,0]
	s_nop 0
	v_fma_f32 v133, -v130, v130, v131
	v_max_f32_e32 v133, 0, v133
	v_add_f32_e32 v133, 0x3727c5ac, v133
	v_mul_f32_e32 v136, 0x4b800000, v133
	v_cmp_gt_f32_e32 vcc, s63, v133
	v_pk_fma_f32 v[124:125], v[84:85], v[130:131], v[124:125] op_sel_hi:[1,0,1] neg_lo:[1,0,0] neg_hi:[1,0,0]
	v_pk_fma_f32 v[126:127], v[176:177], v[130:131], v[126:127] op_sel_hi:[1,0,1]
	v_cndmask_b32_e32 v133, v133, v136, vcc
	v_rsq_f32_e32 v133, v133
	v_pk_fma_f32 v[120:121], v[80:81], v[130:131], v[120:121] op_sel_hi:[1,0,1] neg_lo:[1,0,0] neg_hi:[1,0,0]
	v_pk_fma_f32 v[122:123], v[174:175], v[130:131], v[122:123] op_sel_hi:[1,0,1]
	v_pk_fma_f32 v[116:117], v[92:93], v[130:131], v[116:117] op_sel_hi:[1,0,1] neg_lo:[1,0,0] neg_hi:[1,0,0]
	v_pk_fma_f32 v[118:119], v[94:95], v[130:131], v[118:119] op_sel_hi:[1,0,1]
	v_pk_fma_f32 v[112:113], v[88:89], v[130:131], v[112:113] op_sel_hi:[1,0,1] neg_lo:[1,0,0] neg_hi:[1,0,0]
	v_pk_fma_f32 v[114:115], v[90:91], v[130:131], v[114:115] op_sel_hi:[1,0,1]
	v_mul_f32_e32 v130, 0x45800000, v133
	v_cndmask_b32_e32 v130, v133, v130, vcc
	v_pk_fma_f32 v[126:127], v[126:127], v[130:131], v[160:161] op_sel_hi:[1,0,1]
	v_pk_fma_f32 v[124:125], v[124:125], v[130:131], v[162:163] op_sel_hi:[1,0,1]
	v_pk_fma_f32 v[122:123], v[122:123], v[130:131], v[164:165] op_sel_hi:[1,0,1]
	v_pk_fma_f32 v[120:121], v[120:121], v[130:131], v[166:167] op_sel_hi:[1,0,1]
	v_pk_fma_f32 v[118:119], v[118:119], v[130:131], v[82:83] op_sel_hi:[1,0,1]
	v_pk_fma_f32 v[116:117], v[116:117], v[130:131], v[86:87] op_sel_hi:[1,0,1]
	v_pk_fma_f32 v[114:115], v[114:115], v[130:131], v[168:169] op_sel_hi:[1,0,1]
	v_pk_fma_f32 v[112:113], v[112:113], v[130:131], v[170:171] op_sel_hi:[1,0,1]
	v_max_f32_e32 v124, 0, v124
	v_max_f32_e32 v120, 0, v120
	v_max_f32_e32 v125, 0, v125
	v_max_f32_e32 v121, 0, v121
	v_max_f32_e32 v126, 0, v126
	v_max_f32_e32 v122, 0, v122
	v_max_f32_e32 v127, 0, v127
	v_max_f32_e32 v123, 0, v123
	v_max_f32_e32 v116, 0, v116
	v_max_f32_e32 v112, 0, v112
	v_max_f32_e32 v117, 0, v117
	v_max_f32_e32 v113, 0, v113
	v_max_f32_e32 v118, 0, v118
	v_max_f32_e32 v114, 0, v114
	v_max_f32_e32 v119, 0, v119
	v_max_f32_e32 v115, 0, v115
	v_pk_mul_f32 v[124:125], v[124:125], v[124:125]
	v_pk_mul_f32 v[120:121], v[120:121], v[120:121]
	v_pk_mul_f32 v[126:127], v[126:127], v[126:127]
	v_pk_mul_f32 v[122:123], v[122:123], v[122:123]
	v_pk_mul_f32 v[116:117], v[116:117], v[116:117]
	v_pk_mul_f32 v[130:131], v[112:113], v[112:113]
	v_pk_mul_f32 v[118:119], v[118:119], v[118:119]
	v_pk_mul_f32 v[136:137], v[114:115], v[114:115]
	v_cvt_pk_bf16_f32 v112, v124, v125
	v_cvt_pk_bf16_f32 v113, v126, v127
	v_cvt_pk_bf16_f32 v114, v120, v121
	v_cvt_pk_bf16_f32 v115, v122, v123
	v_cvt_pk_bf16_f32 v116, v116, v117
	v_cvt_pk_bf16_f32 v117, v118, v119
	v_cvt_pk_bf16_f32 v118, v130, v131
	v_cvt_pk_bf16_f32 v119, v136, v137
	global_store_dwordx4 v[128:129], v[112:115], off sc1
	global_store_dwordx4 v[128:129], v[116:119], off offset:256 sc1
	global_load_dwordx2 v[112:113], v[134:135], off
	v_ashrrev_i32_e32 v133, 31, v132
	v_or_b32_e32 v114, 48, v178
	v_lshlrev_b64 v[118:119], 13, v[132:133]
	v_lshlrev_b32_e32 v116, 1, v114
	v_lshl_add_u64 v[118:119], s[4:5], 0, v[118:119]
	v_ashrrev_i32_e32 v117, 31, v116
	v_lshl_add_u64 v[118:119], v[118:119], 0, v[172:173]
	v_lshl_add_u64 v[116:117], v[116:117], 2, s[6:7]
	s_waitcnt vmcnt(0)
	v_pk_mul_f32 v[112:113], v[112:113], s[22:23] op_sel_hi:[1,0]
	s_nop 0
	v_fma_f32 v115, -v112, v112, v113
	v_max_f32_e32 v115, 0, v115
	v_add_f32_e32 v115, 0x3727c5ac, v115
	v_mul_f32_e32 v120, 0x4b800000, v115
	v_cmp_gt_f32_e32 vcc, s63, v115
	v_pk_fma_f32 v[108:109], v[84:85], v[112:113], v[108:109] op_sel_hi:[1,0,1] neg_lo:[1,0,0] neg_hi:[1,0,0]
	v_pk_fma_f32 v[110:111], v[176:177], v[112:113], v[110:111] op_sel_hi:[1,0,1]
	v_cndmask_b32_e32 v115, v115, v120, vcc
	v_rsq_f32_e32 v115, v115
	v_pk_fma_f32 v[104:105], v[80:81], v[112:113], v[104:105] op_sel_hi:[1,0,1] neg_lo:[1,0,0] neg_hi:[1,0,0]
	v_pk_fma_f32 v[106:107], v[174:175], v[112:113], v[106:107] op_sel_hi:[1,0,1]
	v_pk_fma_f32 v[100:101], v[92:93], v[112:113], v[100:101] op_sel_hi:[1,0,1] neg_lo:[1,0,0] neg_hi:[1,0,0]
	v_pk_fma_f32 v[102:103], v[94:95], v[112:113], v[102:103] op_sel_hi:[1,0,1]
	v_pk_fma_f32 v[96:97], v[88:89], v[112:113], v[96:97] op_sel_hi:[1,0,1] neg_lo:[1,0,0] neg_hi:[1,0,0]
	v_pk_fma_f32 v[98:99], v[90:91], v[112:113], v[98:99] op_sel_hi:[1,0,1]
	v_mul_f32_e32 v112, 0x45800000, v115
	v_cndmask_b32_e32 v112, v115, v112, vcc
	v_pk_fma_f32 v[110:111], v[110:111], v[112:113], v[160:161] op_sel_hi:[1,0,1]
	v_pk_fma_f32 v[108:109], v[108:109], v[112:113], v[162:163] op_sel_hi:[1,0,1]
	v_pk_fma_f32 v[106:107], v[106:107], v[112:113], v[164:165] op_sel_hi:[1,0,1]
	v_pk_fma_f32 v[104:105], v[104:105], v[112:113], v[166:167] op_sel_hi:[1,0,1]
	v_pk_fma_f32 v[102:103], v[102:103], v[112:113], v[82:83] op_sel_hi:[1,0,1]
	v_pk_fma_f32 v[100:101], v[100:101], v[112:113], v[86:87] op_sel_hi:[1,0,1]
	v_pk_fma_f32 v[98:99], v[98:99], v[112:113], v[168:169] op_sel_hi:[1,0,1]
	v_pk_fma_f32 v[96:97], v[96:97], v[112:113], v[170:171] op_sel_hi:[1,0,1]
	v_max_f32_e32 v108, 0, v108
	v_max_f32_e32 v104, 0, v104
	v_max_f32_e32 v109, 0, v109
	v_max_f32_e32 v105, 0, v105
	v_max_f32_e32 v110, 0, v110
	v_max_f32_e32 v106, 0, v106
	v_max_f32_e32 v111, 0, v111
	v_max_f32_e32 v107, 0, v107
	v_max_f32_e32 v100, 0, v100
	v_max_f32_e32 v96, 0, v96
	v_max_f32_e32 v101, 0, v101
	v_max_f32_e32 v97, 0, v97
	v_max_f32_e32 v102, 0, v102
	v_max_f32_e32 v98, 0, v98
	v_max_f32_e32 v103, 0, v103
	v_max_f32_e32 v99, 0, v99
	v_pk_mul_f32 v[108:109], v[108:109], v[108:109]
	v_pk_mul_f32 v[104:105], v[104:105], v[104:105]
	v_pk_mul_f32 v[110:111], v[110:111], v[110:111]
	v_pk_mul_f32 v[106:107], v[106:107], v[106:107]
	v_pk_mul_f32 v[100:101], v[100:101], v[100:101]
	v_pk_mul_f32 v[112:113], v[96:97], v[96:97]
	v_pk_mul_f32 v[102:103], v[102:103], v[102:103]
	v_pk_mul_f32 v[120:121], v[98:99], v[98:99]
	v_cvt_pk_bf16_f32 v96, v108, v109
	v_cvt_pk_bf16_f32 v97, v110, v111
	v_cvt_pk_bf16_f32 v98, v104, v105
	v_cvt_pk_bf16_f32 v99, v106, v107
	v_cvt_pk_bf16_f32 v100, v100, v101
	v_cvt_pk_bf16_f32 v101, v102, v103
	v_cvt_pk_bf16_f32 v102, v112, v113
	v_cvt_pk_bf16_f32 v103, v120, v121
	global_store_dwordx4 v[118:119], v[96:99], off sc1
	global_store_dwordx4 v[118:119], v[100:103], off offset:256 sc1
	global_load_dwordx2 v[96:97], v[116:117], off
	v_ashrrev_i32_e32 v115, 31, v114
	v_add_u32_e32 v98, 0x80, v178
	v_lshlrev_b64 v[102:103], 13, v[114:115]
	v_lshlrev_b32_e32 v100, 1, v98
	v_lshl_add_u64 v[102:103], s[4:5], 0, v[102:103]
	v_ashrrev_i32_e32 v101, 31, v100
	v_lshl_add_u64 v[102:103], v[102:103], 0, v[172:173]
	v_lshl_add_u64 v[100:101], v[100:101], 2, s[6:7]
	s_waitcnt vmcnt(0)
; __device__ __forceinline__ unsigned pk2(float lo, float hi) { f32x2v v = {lo, hi}; b16x2v b = __builtin_convertvector(v, b16x2v); return __builtin_bit_cast(unsigned, b); }
;     __device__ __forceinline__ bf16_t* O() const { return (bf16_t*)(ws + WS_O); }
;     __device__ __forceinline__ void operator()(const f32x4 (&acc)[2][2][4][2], const Unit& u, int wr, int wc, int fr, int fq) const {
;     ...
;             for (int m = 0; m < 4; ++m) {
;                 const int row = u.pm * 256 + ai * 128 + wr * 64 + m * 16 + fr;
;                 const f32x2v s2 = *(const f32x2v*)(stp + 2 * row); const float mu = s2.x * (1.0f / DM); const float rs = rsqrtf(fmaxf(s2.y * (1.0f / DM) - mu * mu, 0.f) + LN_EPS);
; #pragma unroll
;                 for (int bj = 0; bj < 2; ++bj) {
;                     f32x4 v0 = (acc[ai][bj][m][0] - c1v[bj][0] * mu) * rs + c2v[bj][0], v1 = (acc[ai][bj][m][1] - c1v[bj][1] * mu) * rs + c2v[bj][1];
;                     if (ACT == 1) {
; #pragma unroll
;                         for (int e = 0; e < 4; ++e) { const float a = fmaxf(v0[e], 0.f), c = fmaxf(v1[e], 0.f); v0[e] = a * a; v1[e] = c * c; }
;                     }
;                     v0 = v0 * scale; v1 = v1 * scale;
;                     u32x4 w; w.x = pk2(v0[0], v0[1]); w.y = pk2(v0[2], v0[3]); w.z = pk2(v1[0], v1[1]); w.w = pk2(v1[2], v1[3]);
;                     *(u32x4*)(O + (size_t)row * ldc + colb + 128 * bj) = w;
;                 }
	v_pk_mul_f32 v[96:97], v[96:97], s[22:23] op_sel_hi:[1,0]
	s_nop 0
	v_fma_f32 v99, -v96, v96, v97
	v_max_f32_e32 v99, 0, v99
	v_add_f32_e32 v99, 0x3727c5ac, v99
	v_mul_f32_e32 v104, 0x4b800000, v99
	v_cmp_gt_f32_e32 vcc, s63, v99
	v_pk_fma_f32 v[76:77], v[84:85], v[96:97], v[76:77] op_sel_hi:[1,0,1] neg_lo:[1,0,0] neg_hi:[1,0,0]
	v_pk_fma_f32 v[78:79], v[176:177], v[96:97], v[78:79] op_sel_hi:[1,0,1]
	v_cndmask_b32_e32 v99, v99, v104, vcc
	v_rsq_f32_e32 v99, v99
	v_pk_fma_f32 v[72:73], v[80:81], v[96:97], v[72:73] op_sel_hi:[1,0,1] neg_lo:[1,0,0] neg_hi:[1,0,0]
	v_pk_fma_f32 v[74:75], v[174:175], v[96:97], v[74:75] op_sel_hi:[1,0,1]
	v_pk_fma_f32 v[68:69], v[92:93], v[96:97], v[68:69] op_sel_hi:[1,0,1] neg_lo:[1,0,0] neg_hi:[1,0,0]
	v_pk_fma_f32 v[70:71], v[94:95], v[96:97], v[70:71] op_sel_hi:[1,0,1]
	v_pk_fma_f32 v[64:65], v[88:89], v[96:97], v[64:65] op_sel_hi:[1,0,1] neg_lo:[1,0,0] neg_hi:[1,0,0]
	v_pk_fma_f32 v[66:67], v[90:91], v[96:97], v[66:67] op_sel_hi:[1,0,1]
	v_mul_f32_e32 v96, 0x45800000, v99
	v_cndmask_b32_e32 v96, v99, v96, vcc
	v_pk_fma_f32 v[78:79], v[78:79], v[96:97], v[160:161] op_sel_hi:[1,0,1]
	v_pk_fma_f32 v[76:77], v[76:77], v[96:97], v[162:163] op_sel_hi:[1,0,1]
	v_pk_fma_f32 v[74:75], v[74:75], v[96:97], v[164:165] op_sel_hi:[1,0,1]
	v_pk_fma_f32 v[72:73], v[72:73], v[96:97], v[166:167] op_sel_hi:[1,0,1]
	v_pk_fma_f32 v[70:71], v[70:71], v[96:97], v[82:83] op_sel_hi:[1,0,1]
	v_pk_fma_f32 v[68:69], v[68:69], v[96:97], v[86:87] op_sel_hi:[1,0,1]
	v_pk_fma_f32 v[66:67], v[66:67], v[96:97], v[168:169] op_sel_hi:[1,0,1]
	v_pk_fma_f32 v[64:65], v[64:65], v[96:97], v[170:171] op_sel_hi:[1,0,1]
	v_max_f32_e32 v76, 0, v76
	v_max_f32_e32 v72, 0, v72
	v_max_f32_e32 v77, 0, v77
	v_max_f32_e32 v73, 0, v73
	v_max_f32_e32 v78, 0, v78
	v_max_f32_e32 v74, 0, v74
	v_max_f32_e32 v79, 0, v79
	v_max_f32_e32 v75, 0, v75
	v_max_f32_e32 v68, 0, v68
	v_max_f32_e32 v64, 0, v64
	v_max_f32_e32 v69, 0, v69
	v_max_f32_e32 v65, 0, v65
	v_max_f32_e32 v70, 0, v70
	v_max_f32_e32 v66, 0, v66
	v_max_f32_e32 v71, 0, v71
	v_max_f32_e32 v67, 0, v67
	v_pk_mul_f32 v[76:77], v[76:77], v[76:77]
	v_pk_mul_f32 v[72:73], v[72:73], v[72:73]
	v_pk_mul_f32 v[78:79], v[78:79], v[78:79]
	v_pk_mul_f32 v[74:75], v[74:75], v[74:75]
	v_pk_mul_f32 v[68:69], v[68:69], v[68:69]
	v_pk_mul_f32 v[96:97], v[64:65], v[64:65]
	v_pk_mul_f32 v[70:71], v[70:71], v[70:71]
	v_pk_mul_f32 v[104:105], v[66:67], v[66:67]
	v_cvt_pk_bf16_f32 v64, v76, v77
	v_cvt_pk_bf16_f32 v65, v78, v79
	v_cvt_pk_bf16_f32 v66, v72, v73
	v_cvt_pk_bf16_f32 v67, v74, v75
	v_cvt_pk_bf16_f32 v68, v68, v69
	v_cvt_pk_bf16_f32 v69, v70, v71
	v_cvt_pk_bf16_f32 v70, v96, v97
	v_cvt_pk_bf16_f32 v71, v104, v105
	global_store_dwordx4 v[102:103], v[64:67], off sc1
	global_store_dwordx4 v[102:103], v[68:71], off offset:256 sc1
	global_load_dwordx2 v[64:65], v[100:101], off
	v_ashrrev_i32_e32 v99, 31, v98
	v_add_u32_e32 v66, 0x90, v178
	v_lshlrev_b64 v[70:71], 13, v[98:99]
	v_lshlrev_b32_e32 v68, 1, v66
	v_lshl_add_u64 v[70:71], s[4:5], 0, v[70:71]
	v_ashrrev_i32_e32 v69, 31, v68
	v_lshl_add_u64 v[70:71], v[70:71], 0, v[172:173]
	v_lshl_add_u64 v[68:69], v[68:69], 2, s[6:7]
	s_waitcnt vmcnt(0)
	v_pk_mul_f32 v[64:65], v[64:65], s[22:23] op_sel_hi:[1,0]
	s_nop 0
	v_fma_f32 v67, -v64, v64, v65
	v_max_f32_e32 v67, 0, v67
	v_add_f32_e32 v67, 0x3727c5ac, v67
	v_mul_f32_e32 v72, 0x4b800000, v67
	v_cmp_gt_f32_e32 vcc, s63, v67
	v_pk_fma_f32 v[60:61], v[84:85], v[64:65], v[60:61] op_sel_hi:[1,0,1] neg_lo:[1,0,0] neg_hi:[1,0,0]
	v_pk_fma_f32 v[62:63], v[176:177], v[64:65], v[62:63] op_sel_hi:[1,0,1]
	v_cndmask_b32_e32 v67, v67, v72, vcc
	v_rsq_f32_e32 v67, v67
	v_pk_fma_f32 v[56:57], v[80:81], v[64:65], v[56:57] op_sel_hi:[1,0,1] neg_lo:[1,0,0] neg_hi:[1,0,0]
	v_pk_fma_f32 v[58:59], v[174:175], v[64:65], v[58:59] op_sel_hi:[1,0,1]
	v_pk_fma_f32 v[52:53], v[92:93], v[64:65], v[52:53] op_sel_hi:[1,0,1] neg_lo:[1,0,0] neg_hi:[1,0,0]
	v_pk_fma_f32 v[54:55], v[94:95], v[64:65], v[54:55] op_sel_hi:[1,0,1]
	v_pk_fma_f32 v[48:49], v[88:89], v[64:65], v[48:49] op_sel_hi:[1,0,1] neg_lo:[1,0,0] neg_hi:[1,0,0]
	v_pk_fma_f32 v[50:51], v[90:91], v[64:65], v[50:51] op_sel_hi:[1,0,1]
	v_mul_f32_e32 v64, 0x45800000, v67
	v_cndmask_b32_e32 v64, v67, v64, vcc
	v_pk_fma_f32 v[62:63], v[62:63], v[64:65], v[160:161] op_sel_hi:[1,0,1]
	v_pk_fma_f32 v[60:61], v[60:61], v[64:65], v[162:163] op_sel_hi:[1,0,1]
	v_pk_fma_f32 v[58:59], v[58:59], v[64:65], v[164:165] op_sel_hi:[1,0,1]
	v_pk_fma_f32 v[56:57], v[56:57], v[64:65], v[166:167] op_sel_hi:[1,0,1]
	v_pk_fma_f32 v[54:55], v[54:55], v[64:65], v[82:83] op_sel_hi:[1,0,1]
	v_pk_fma_f32 v[52:53], v[52:53], v[64:65], v[86:87] op_sel_hi:[1,0,1]
	v_pk_fma_f32 v[50:51], v[50:51], v[64:65], v[168:169] op_sel_hi:[1,0,1]
	v_pk_fma_f32 v[48:49], v[48:49], v[64:65], v[170:171] op_sel_hi:[1,0,1]
	v_max_f32_e32 v60, 0, v60
	v_max_f32_e32 v56, 0, v56
	v_max_f32_e32 v61, 0, v61
	v_max_f32_e32 v57, 0, v57
	v_max_f32_e32 v62, 0, v62
	v_max_f32_e32 v58, 0, v58
	v_max_f32_e32 v63, 0, v63
	v_max_f32_e32 v59, 0, v59
	v_max_f32_e32 v52, 0, v52
	v_max_f32_e32 v48, 0, v48
	v_max_f32_e32 v53, 0, v53
	v_max_f32_e32 v49, 0, v49
	v_max_f32_e32 v54, 0, v54
	v_max_f32_e32 v50, 0, v50
	v_max_f32_e32 v55, 0, v55
	v_max_f32_e32 v51, 0, v51
	v_pk_mul_f32 v[60:61], v[60:61], v[60:61]
	v_pk_mul_f32 v[56:57], v[56:57], v[56:57]
	v_pk_mul_f32 v[62:63], v[62:63], v[62:63]
	v_pk_mul_f32 v[58:59], v[58:59], v[58:59]
	v_pk_mul_f32 v[52:53], v[52:53], v[52:53]
	v_pk_mul_f32 v[64:65], v[48:49], v[48:49]
	v_pk_mul_f32 v[54:55], v[54:55], v[54:55]
	v_pk_mul_f32 v[72:73], v[50:51], v[50:51]
	v_cvt_pk_bf16_f32 v48, v60, v61
	v_cvt_pk_bf16_f32 v49, v62, v63
	v_cvt_pk_bf16_f32 v50, v56, v57
	v_cvt_pk_bf16_f32 v51, v58, v59
	v_cvt_pk_bf16_f32 v52, v52, v53
	v_cvt_pk_bf16_f32 v53, v54, v55
	v_cvt_pk_bf16_f32 v54, v64, v65
	v_cvt_pk_bf16_f32 v55, v72, v73
	global_store_dwordx4 v[70:71], v[48:51], off sc1
	global_store_dwordx4 v[70:71], v[52:55], off offset:256 sc1
	global_load_dwordx2 v[48:49], v[68:69], off
	v_ashrrev_i32_e32 v67, 31, v66
	v_add_u32_e32 v50, 0xa0, v178
	v_lshlrev_b64 v[54:55], 13, v[66:67]
	v_lshlrev_b32_e32 v52, 1, v50
	v_lshl_add_u64 v[54:55], s[4:5], 0, v[54:55]
	v_ashrrev_i32_e32 v53, 31, v52
	v_lshl_add_u64 v[54:55], v[54:55], 0, v[172:173]
	v_lshl_add_u64 v[52:53], v[52:53], 2, s[6:7]
	s_waitcnt vmcnt(0)
; __device__ __forceinline__ unsigned pk2(float lo, float hi) { f32x2v v = {lo, hi}; b16x2v b = __builtin_convertvector(v, b16x2v); return __builtin_bit_cast(unsigned, b); }
;     __device__ __forceinline__ bf16_t* O() const { return (bf16_t*)(ws + WS_O); }
;     __device__ __forceinline__ void operator()(const f32x4 (&acc)[2][2][4][2], const Unit& u, int wr, int wc, int fr, int fq) const {
;     ...
;             for (int m = 0; m < 4; ++m) {
;                 const int row = u.pm * 256 + ai * 128 + wr * 64 + m * 16 + fr;
;                 const f32x2v s2 = *(const f32x2v*)(stp + 2 * row); const float mu = s2.x * (1.0f / DM); const float rs = rsqrtf(fmaxf(s2.y * (1.0f / DM) - mu * mu, 0.f) + LN_EPS);
; #pragma unroll
;                 for (int bj = 0; bj < 2; ++bj) {
;                     f32x4 v0 = (acc[ai][bj][m][0] - c1v[bj][0] * mu) * rs + c2v[bj][0], v1 = (acc[ai][bj][m][1] - c1v[bj][1] * mu) * rs + c2v[bj][1];
;                     if (ACT == 1) {
; #pragma unroll
;                         for (int e = 0; e < 4; ++e) { const float a = fmaxf(v0[e], 0.f), c = fmaxf(v1[e], 0.f); v0[e] = a * a; v1[e] = c * c; }
;                     }
;                     v0 = v0 * scale; v1 = v1 * scale;
;                     u32x4 w; w.x = pk2(v0[0], v0[1]); w.y = pk2(v0[2], v0[3]); w.z = pk2(v1[0], v1[1]); w.w = pk2(v1[2], v1[3]);
;                     *(u32x4*)(O + (size_t)row * ldc + colb + 128 * bj) = w;
;                 }
	v_pk_mul_f32 v[48:49], v[48:49], s[22:23] op_sel_hi:[1,0]
	s_nop 0
	v_fma_f32 v51, -v48, v48, v49
	v_max_f32_e32 v51, 0, v51
	v_add_f32_e32 v51, 0x3727c5ac, v51
	v_mul_f32_e32 v56, 0x4b800000, v51
	v_cmp_gt_f32_e32 vcc, s63, v51
	v_pk_fma_f32 v[44:45], v[84:85], v[48:49], v[44:45] op_sel_hi:[1,0,1] neg_lo:[1,0,0] neg_hi:[1,0,0]
	v_pk_fma_f32 v[46:47], v[176:177], v[48:49], v[46:47] op_sel_hi:[1,0,1]
	v_cndmask_b32_e32 v51, v51, v56, vcc
	v_rsq_f32_e32 v51, v51
	v_pk_fma_f32 v[40:41], v[80:81], v[48:49], v[40:41] op_sel_hi:[1,0,1] neg_lo:[1,0,0] neg_hi:[1,0,0]
	v_pk_fma_f32 v[42:43], v[174:175], v[48:49], v[42:43] op_sel_hi:[1,0,1]
	v_pk_fma_f32 v[36:37], v[92:93], v[48:49], v[36:37] op_sel_hi:[1,0,1] neg_lo:[1,0,0] neg_hi:[1,0,0]
	v_pk_fma_f32 v[38:39], v[94:95], v[48:49], v[38:39] op_sel_hi:[1,0,1]
	v_pk_fma_f32 v[32:33], v[88:89], v[48:49], v[32:33] op_sel_hi:[1,0,1] neg_lo:[1,0,0] neg_hi:[1,0,0]
	v_pk_fma_f32 v[34:35], v[90:91], v[48:49], v[34:35] op_sel_hi:[1,0,1]
	v_mul_f32_e32 v48, 0x45800000, v51
	v_cndmask_b32_e32 v48, v51, v48, vcc
	v_pk_fma_f32 v[46:47], v[46:47], v[48:49], v[160:161] op_sel_hi:[1,0,1]
	v_pk_fma_f32 v[44:45], v[44:45], v[48:49], v[162:163] op_sel_hi:[1,0,1]
	v_pk_fma_f32 v[42:43], v[42:43], v[48:49], v[164:165] op_sel_hi:[1,0,1]
	v_pk_fma_f32 v[40:41], v[40:41], v[48:49], v[166:167] op_sel_hi:[1,0,1]
	v_pk_fma_f32 v[38:39], v[38:39], v[48:49], v[82:83] op_sel_hi:[1,0,1]
	v_pk_fma_f32 v[36:37], v[36:37], v[48:49], v[86:87] op_sel_hi:[1,0,1]
	v_pk_fma_f32 v[34:35], v[34:35], v[48:49], v[168:169] op_sel_hi:[1,0,1]
	v_pk_fma_f32 v[32:33], v[32:33], v[48:49], v[170:171] op_sel_hi:[1,0,1]
	v_max_f32_e32 v44, 0, v44
	v_max_f32_e32 v40, 0, v40
	v_max_f32_e32 v45, 0, v45
	v_max_f32_e32 v41, 0, v41
	v_max_f32_e32 v46, 0, v46
	v_max_f32_e32 v42, 0, v42
	v_max_f32_e32 v47, 0, v47
	v_max_f32_e32 v43, 0, v43
	v_max_f32_e32 v36, 0, v36
	v_max_f32_e32 v32, 0, v32
	v_max_f32_e32 v37, 0, v37
	v_max_f32_e32 v33, 0, v33
	v_max_f32_e32 v38, 0, v38
	v_max_f32_e32 v34, 0, v34
	v_max_f32_e32 v39, 0, v39
	v_max_f32_e32 v35, 0, v35
	v_pk_mul_f32 v[44:45], v[44:45], v[44:45]
	v_pk_mul_f32 v[40:41], v[40:41], v[40:41]
	v_pk_mul_f32 v[46:47], v[46:47], v[46:47]
	v_pk_mul_f32 v[42:43], v[42:43], v[42:43]
	v_pk_mul_f32 v[36:37], v[36:37], v[36:37]
	v_pk_mul_f32 v[48:49], v[32:33], v[32:33]
	v_pk_mul_f32 v[38:39], v[38:39], v[38:39]
	v_pk_mul_f32 v[56:57], v[34:35], v[34:35]
	v_cvt_pk_bf16_f32 v32, v44, v45
	v_cvt_pk_bf16_f32 v33, v46, v47
	v_cvt_pk_bf16_f32 v34, v40, v41
	v_cvt_pk_bf16_f32 v35, v42, v43
	v_cvt_pk_bf16_f32 v36, v36, v37
	v_cvt_pk_bf16_f32 v37, v38, v39
	v_cvt_pk_bf16_f32 v38, v48, v49
	v_cvt_pk_bf16_f32 v39, v56, v57
	global_store_dwordx4 v[54:55], v[32:35], off sc1
	global_store_dwordx4 v[54:55], v[36:39], off offset:256 sc1
	global_load_dwordx2 v[32:33], v[52:53], off
	v_ashrrev_i32_e32 v51, 31, v50
	v_add_u32_e32 v34, 0xb0, v178
	v_lshlrev_b64 v[38:39], 13, v[50:51]
	v_lshlrev_b32_e32 v36, 1, v34
	v_lshl_add_u64 v[38:39], s[4:5], 0, v[38:39]
	v_ashrrev_i32_e32 v37, 31, v36
	v_lshl_add_u64 v[38:39], v[38:39], 0, v[172:173]
	v_lshl_add_u64 v[36:37], v[36:37], 2, s[6:7]
	s_waitcnt vmcnt(0)
; __device__ __forceinline__ unsigned pk2(float lo, float hi) { f32x2v v = {lo, hi}; b16x2v b = __builtin_convertvector(v, b16x2v); return __builtin_bit_cast(unsigned, b); }
;     __device__ __forceinline__ bf16_t* O() const { return (bf16_t*)(ws + WS_O); }
;     __device__ __forceinline__ void operator()(const f32x4 (&acc)[2][2][4][2], const Unit& u, int wr, int wc, int fr, int fq) const {
;     ...
;             for (int m = 0; m < 4; ++m) {
;                 const int row = u.pm * 256 + ai * 128 + wr * 64 + m * 16 + fr;
;                 const f32x2v s2 = *(const f32x2v*)(stp + 2 * row); const float mu = s2.x * (1.0f / DM); const float rs = rsqrtf(fmaxf(s2.y * (1.0f / DM) - mu * mu, 0.f) + LN_EPS);
; #pragma unroll
;                 for (int bj = 0; bj < 2; ++bj) {
;                     f32x4 v0 = (acc[ai][bj][m][0] - c1v[bj][0] * mu) * rs + c2v[bj][0], v1 = (acc[ai][bj][m][1] - c1v[bj][1] * mu) * rs + c2v[bj][1];
;                     if (ACT == 1) {
; #pragma unroll
;                         for (int e = 0; e < 4; ++e) { const float a = fmaxf(v0[e], 0.f), c = fmaxf(v1[e], 0.f); v0[e] = a * a; v1[e] = c * c; }
;                     }
;                     v0 = v0 * scale; v1 = v1 * scale;
;                     u32x4 w; w.x = pk2(v0[0], v0[1]); w.y = pk2(v0[2], v0[3]); w.z = pk2(v1[0], v1[1]); w.w = pk2(v1[2], v1[3]);
;                     *(u32x4*)(O + (size_t)row * ldc + colb + 128 * bj) = w;
;                 }
	v_pk_mul_f32 v[32:33], v[32:33], s[22:23] op_sel_hi:[1,0]
	s_nop 0
	v_fma_f32 v35, -v32, v32, v33
	v_max_f32_e32 v35, 0, v35
	v_add_f32_e32 v35, 0x3727c5ac, v35
	v_mul_f32_e32 v40, 0x4b800000, v35
	v_cmp_gt_f32_e32 vcc, s63, v35
	v_pk_fma_f32 v[28:29], v[84:85], v[32:33], v[28:29] op_sel_hi:[1,0,1] neg_lo:[1,0,0] neg_hi:[1,0,0]
	v_pk_fma_f32 v[30:31], v[176:177], v[32:33], v[30:31] op_sel_hi:[1,0,1]
	v_cndmask_b32_e32 v35, v35, v40, vcc
	v_rsq_f32_e32 v35, v35
	v_pk_fma_f32 v[24:25], v[80:81], v[32:33], v[24:25] op_sel_hi:[1,0,1] neg_lo:[1,0,0] neg_hi:[1,0,0]
	v_pk_fma_f32 v[26:27], v[174:175], v[32:33], v[26:27] op_sel_hi:[1,0,1]
	v_pk_fma_f32 v[20:21], v[92:93], v[32:33], v[20:21] op_sel_hi:[1,0,1] neg_lo:[1,0,0] neg_hi:[1,0,0]
	v_pk_fma_f32 v[22:23], v[94:95], v[32:33], v[22:23] op_sel_hi:[1,0,1]
	v_pk_fma_f32 v[16:17], v[88:89], v[32:33], v[16:17] op_sel_hi:[1,0,1] neg_lo:[1,0,0] neg_hi:[1,0,0]
	v_pk_fma_f32 v[18:19], v[90:91], v[32:33], v[18:19] op_sel_hi:[1,0,1]
	v_mul_f32_e32 v32, 0x45800000, v35
	v_cndmask_b32_e32 v32, v35, v32, vcc
	v_pk_fma_f32 v[30:31], v[30:31], v[32:33], v[160:161] op_sel_hi:[1,0,1]
	v_pk_fma_f32 v[28:29], v[28:29], v[32:33], v[162:163] op_sel_hi:[1,0,1]
	v_pk_fma_f32 v[26:27], v[26:27], v[32:33], v[164:165] op_sel_hi:[1,0,1]
	v_pk_fma_f32 v[24:25], v[24:25], v[32:33], v[166:167] op_sel_hi:[1,0,1]
	v_pk_fma_f32 v[22:23], v[22:23], v[32:33], v[82:83] op_sel_hi:[1,0,1]
	v_pk_fma_f32 v[20:21], v[20:21], v[32:33], v[86:87] op_sel_hi:[1,0,1]
	v_pk_fma_f32 v[18:19], v[18:19], v[32:33], v[168:169] op_sel_hi:[1,0,1]
	v_pk_fma_f32 v[16:17], v[16:17], v[32:33], v[170:171] op_sel_hi:[1,0,1]
	v_max_f32_e32 v28, 0, v28
	v_max_f32_e32 v24, 0, v24
	v_max_f32_e32 v29, 0, v29
	v_max_f32_e32 v25, 0, v25
	v_max_f32_e32 v30, 0, v30
	v_max_f32_e32 v26, 0, v26
	v_max_f32_e32 v31, 0, v31
	v_max_f32_e32 v27, 0, v27
	v_max_f32_e32 v20, 0, v20
	v_max_f32_e32 v16, 0, v16
	v_max_f32_e32 v21, 0, v21
	v_max_f32_e32 v17, 0, v17
	v_max_f32_e32 v22, 0, v22
	v_max_f32_e32 v18, 0, v18
	v_max_f32_e32 v23, 0, v23
	v_max_f32_e32 v19, 0, v19
	v_pk_mul_f32 v[28:29], v[28:29], v[28:29]
	v_pk_mul_f32 v[24:25], v[24:25], v[24:25]
	v_pk_mul_f32 v[30:31], v[30:31], v[30:31]
	v_pk_mul_f32 v[26:27], v[26:27], v[26:27]
	v_pk_mul_f32 v[20:21], v[20:21], v[20:21]
	v_pk_mul_f32 v[32:33], v[16:17], v[16:17]
	v_pk_mul_f32 v[22:23], v[22:23], v[22:23]
	v_pk_mul_f32 v[40:41], v[18:19], v[18:19]
	v_cvt_pk_bf16_f32 v16, v28, v29
	v_cvt_pk_bf16_f32 v17, v30, v31
	v_cvt_pk_bf16_f32 v18, v24, v25
	v_cvt_pk_bf16_f32 v19, v26, v27
	v_cvt_pk_bf16_f32 v20, v20, v21
	v_cvt_pk_bf16_f32 v21, v22, v23
	v_cvt_pk_bf16_f32 v22, v32, v33
	v_cvt_pk_bf16_f32 v23, v40, v41
	global_store_dwordx4 v[38:39], v[16:19], off sc1
	global_store_dwordx4 v[38:39], v[20:23], off offset:256 sc1
	global_load_dwordx2 v[16:17], v[36:37], off
	v_ashrrev_i32_e32 v35, 31, v34
	v_lshlrev_b64 v[18:19], 13, v[34:35]
	v_lshl_add_u64 v[18:19], s[4:5], 0, v[18:19]
	s_andn2_b64 vcc, exec, s[2:3]
	v_lshl_add_u64 v[18:19], v[18:19], 0, v[172:173]
	s_waitcnt vmcnt(0)
	v_pk_mul_f32 v[16:17], v[16:17], s[22:23] op_sel_hi:[1,0]
	s_nop 0
	v_fma_f32 v20, -v16, v16, v17
	v_max_f32_e32 v20, 0, v20
	v_add_f32_e32 v20, 0x3727c5ac, v20
	v_mul_f32_e32 v21, 0x4b800000, v20
	v_cmp_gt_f32_e64 s[0:1], s63, v20
	v_pk_fma_f32 v[12:13], v[84:85], v[16:17], v[12:13] op_sel_hi:[1,0,1] neg_lo:[1,0,0] neg_hi:[1,0,0]
	v_pk_fma_f32 v[14:15], v[176:177], v[16:17], v[14:15] op_sel_hi:[1,0,1]
	v_cndmask_b32_e64 v20, v20, v21, s[0:1]
	v_rsq_f32_e32 v20, v20
	v_pk_fma_f32 v[8:9], v[80:81], v[16:17], v[8:9] op_sel_hi:[1,0,1] neg_lo:[1,0,0] neg_hi:[1,0,0]
	v_pk_fma_f32 v[10:11], v[174:175], v[16:17], v[10:11] op_sel_hi:[1,0,1]
	v_pk_fma_f32 v[4:5], v[92:93], v[16:17], v[4:5] op_sel_hi:[1,0,1] neg_lo:[1,0,0] neg_hi:[1,0,0]
	v_pk_fma_f32 v[6:7], v[94:95], v[16:17], v[6:7] op_sel_hi:[1,0,1]
	v_pk_fma_f32 v[0:1], v[88:89], v[16:17], v[0:1] op_sel_hi:[1,0,1] neg_lo:[1,0,0] neg_hi:[1,0,0]
	v_pk_fma_f32 v[2:3], v[90:91], v[16:17], v[2:3] op_sel_hi:[1,0,1]
	v_mul_f32_e32 v16, 0x45800000, v20
	v_cndmask_b32_e64 v16, v20, v16, s[0:1]
	v_pk_fma_f32 v[14:15], v[14:15], v[16:17], v[160:161] op_sel_hi:[1,0,1]
	v_pk_fma_f32 v[12:13], v[12:13], v[16:17], v[162:163] op_sel_hi:[1,0,1]
	v_pk_fma_f32 v[10:11], v[10:11], v[16:17], v[164:165] op_sel_hi:[1,0,1]
	v_pk_fma_f32 v[8:9], v[8:9], v[16:17], v[166:167] op_sel_hi:[1,0,1]
	v_pk_fma_f32 v[6:7], v[6:7], v[16:17], v[82:83] op_sel_hi:[1,0,1]
	v_pk_fma_f32 v[4:5], v[4:5], v[16:17], v[86:87] op_sel_hi:[1,0,1]
	v_pk_fma_f32 v[2:3], v[2:3], v[16:17], v[168:169] op_sel_hi:[1,0,1]
	v_pk_fma_f32 v[0:1], v[0:1], v[16:17], v[170:171] op_sel_hi:[1,0,1]
	v_max_f32_e32 v12, 0, v12
	v_max_f32_e32 v8, 0, v8
	v_max_f32_e32 v13, 0, v13
	v_max_f32_e32 v9, 0, v9
	v_max_f32_e32 v14, 0, v14
	v_max_f32_e32 v10, 0, v10
	v_max_f32_e32 v15, 0, v15
	v_max_f32_e32 v11, 0, v11
	v_max_f32_e32 v4, 0, v4
	v_max_f32_e32 v0, 0, v0
	v_max_f32_e32 v5, 0, v5
	v_max_f32_e32 v1, 0, v1
	v_max_f32_e32 v6, 0, v6
	v_max_f32_e32 v2, 0, v2
	v_max_f32_e32 v7, 0, v7
	v_max_f32_e32 v3, 0, v3
	v_pk_mul_f32 v[12:13], v[12:13], v[12:13]
	v_pk_mul_f32 v[8:9], v[8:9], v[8:9]
	v_pk_mul_f32 v[14:15], v[14:15], v[14:15]
	v_pk_mul_f32 v[10:11], v[10:11], v[10:11]
	v_pk_mul_f32 v[4:5], v[4:5], v[4:5]
	v_pk_mul_f32 v[16:17], v[0:1], v[0:1]
	v_pk_mul_f32 v[6:7], v[6:7], v[6:7]
	v_pk_mul_f32 v[20:21], v[2:3], v[2:3]
	v_cvt_pk_bf16_f32 v0, v12, v13
	v_cvt_pk_bf16_f32 v1, v14, v15
	v_cvt_pk_bf16_f32 v2, v8, v9
	v_cvt_pk_bf16_f32 v3, v10, v11
	s_mov_b64 s[0:1], -1
	v_cvt_pk_bf16_f32 v4, v4, v5
	v_cvt_pk_bf16_f32 v5, v6, v7
	v_cvt_pk_bf16_f32 v6, v16, v17
	v_cvt_pk_bf16_f32 v7, v20, v21
	global_store_dwordx4 v[18:19], v[0:3], off sc1
	global_store_dwordx4 v[18:19], v[4:7], off offset:256 sc1
	s_cbranch_vccnz .LBB0_1112
	s_andn2_b64 vcc, exec, s[16:17]
	s_cbranch_vccnz .LBB0_1111
	s_barrier
	s_branch .LBB0_1111

; __device__ __forceinline__ unsigned pk2(float lo, float hi) { f32x2v v = {lo, hi}; b16x2v b = __builtin_convertvector(v, b16x2v); return __builtin_bit_cast(unsigned, b); }
;     __device__ __forceinline__ bf16_t* O() const { return (bf16_t*)(ws + WS_O); }
;     __device__ __forceinline__ void operator()(int row, int colb, int fq, f32x4 acc0, f32x4 acc1, int nt) const {
;         const f32x2v s2 = *(const f32x2v*)(stp + 2 * row); const float mu = s2.x * (1.0f / DM); const float rs = rsqrtf(fmaxf(s2.y * (1.0f / DM) - mu * mu, 0.f) + LN_EPS);
; #pragma unroll
;         for (int t = 0; t < 2; ++t) { if (t >= nt) break; const int col = colb + 16 * t + 4 * fq;
;             f32x4 c2v = *(const f32x4*)(c2 + col); if (HAS_BIAS) c2v = c2v + *(const f32x4*)(bias + col);
;             f32x4 v = ((t ? acc1 : acc0) - *(const f32x4*)(c1 + col) * mu) * rs + c2v;
;             if (ACT == 1) {
; #pragma unroll
;                 for (int e = 0; e < 4; ++e) { const float a = fmaxf(v[e], 0.f); v[e] = a * a; }
;             }
;             v = v * scale;
;             u32x2 w; w.x = pk2(v[0], v[1]); w.y = pk2(v[2], v[3]);
;             *(u32x2*)(O + (size_t)row * ldc + col) = w; }
;     }
.LBB0_1130:
	s_waitcnt vmcnt(5)
	v_add_u32_e32 v16, s14, v94
	v_or_b32_e32 v72, s13, v103
	v_lshlrev_b32_e32 v6, 3, v16
	v_lshlrev_b64 v[8:9], 2, v[72:73]
	v_lshl_add_u64 v[4:5], s[10:11], 0, v[8:9]
	global_load_dwordx2 v[12:13], v6, s[6:7]
	global_load_dwordx4 v[0:3], v[4:5], off
	v_lshl_add_u64 v[14:15], s[46:47], 0, v[8:9]
	global_load_dwordx4 v[4:7], v[14:15], off
	v_lshl_add_u64 v[8:9], s[8:9], 0, v[8:9]
	global_load_dwordx4 v[8:11], v[8:9], off
	v_mov_b32_e32 v17, v73
	v_lshlrev_b32_e32 v16, 13, v16
	v_mov_b32_e32 v19, v73
	v_lshlrev_b32_e32 v18, 1, v72
	v_or_b32_e32 v72, 16, v72
	v_lshl_add_u64 v[16:17], s[4:5], 0, v[16:17]
	v_lshlrev_b64 v[20:21], 2, v[72:73]
	v_lshl_add_u64 v[16:17], v[16:17], 0, v[18:19]
	v_lshl_add_u64 v[18:19], s[10:11], 0, v[20:21]
	s_add_i32 s12, s12, s96
	s_cmpk_gt_i32 s12, 0x1ff
	s_waitcnt vmcnt(3)
	v_pk_mul_f32 v[12:13], v[12:13], s[0:1] op_sel_hi:[1,0]
	s_nop 0
	v_fma_f32 v22, -v12, v12, v13
	s_waitcnt vmcnt(1)
	v_pk_add_f32 v[0:1], v[0:1], v[4:5]
	v_max_f32_e32 v4, 0, v22
	v_add_f32_e32 v4, 0x3727c5ac, v4
	v_pk_add_f32 v[2:3], v[2:3], v[6:7]
	v_mul_f32_e32 v6, 0x4b800000, v4
	v_cmp_gt_f32_e32 vcc, s1, v4
	s_waitcnt vmcnt(0)
	v_xor_b32_e32 v5, 0x80000000, v11
	v_cndmask_b32_e32 v4, v4, v6, vcc
	v_rsq_f32_e32 v11, v4
	v_xor_b32_e32 v4, 0x80000000, v10
	v_pk_fma_f32 v[6:7], v[8:9], v[12:13], v[68:69] op_sel_hi:[1,0,1] neg_lo:[1,0,0] neg_hi:[1,0,0]
	v_pk_fma_f32 v[4:5], v[4:5], v[12:13], v[70:71] op_sel_hi:[1,0,1]
	v_mul_f32_e32 v8, 0x45800000, v11
	v_cndmask_b32_e32 v22, v11, v8, vcc
	v_pk_fma_f32 v[2:3], v[4:5], v[22:23], v[2:3] op_sel_hi:[1,0,1]
	v_pk_fma_f32 v[0:1], v[6:7], v[22:23], v[0:1] op_sel_hi:[1,0,1]
	v_max_f32_e32 v2, 0, v2
	v_max_f32_e32 v0, 0, v0
	v_max_f32_e32 v1, 0, v1
	v_max_f32_e32 v3, 0, v3
	v_pk_mul_f32 v[0:1], v[0:1], v[0:1]
	v_pk_mul_f32 v[2:3], v[2:3], v[2:3]
	v_cvt_pk_bf16_f32 v0, v0, v1
	v_cvt_pk_bf16_f32 v1, v2, v3
	global_store_dwordx2 v[16:17], v[0:1], off sc1
	v_lshl_add_u64 v[8:9], s[8:9], 0, v[20:21]
	global_load_dwordx4 v[0:3], v[18:19], off
	global_load_dwordx4 v[4:7], v[14:15], off offset:64
	s_waitcnt vmcnt(0)
	v_pk_add_f32 v[2:3], v[2:3], v[6:7]
	global_load_dwordx4 v[8:11], v[8:9], off
	v_pk_add_f32 v[0:1], v[0:1], v[4:5]
	s_waitcnt vmcnt(0)
	v_pk_fma_f32 v[4:5], v[12:13], v[10:11], v[66:67] op_sel_hi:[0,1,1] neg_lo:[1,0,0] neg_hi:[1,0,0]
	v_pk_fma_f32 v[6:7], v[12:13], v[8:9], v[64:65] op_sel_hi:[0,1,1] neg_lo:[1,0,0] neg_hi:[1,0,0]
	v_pk_fma_f32 v[2:3], v[4:5], v[22:23], v[2:3] op_sel_hi:[1,0,1]
	v_pk_fma_f32 v[0:1], v[6:7], v[22:23], v[0:1] op_sel_hi:[1,0,1]
	v_max_f32_e32 v2, 0, v2
	v_max_f32_e32 v0, 0, v0
	v_max_f32_e32 v1, 0, v1
	v_max_f32_e32 v3, 0, v3
	v_pk_mul_f32 v[0:1], v[0:1], v[0:1]
	v_pk_mul_f32 v[2:3], v[2:3], v[2:3]
	v_cvt_pk_bf16_f32 v0, v0, v1
	v_cvt_pk_bf16_f32 v1, v2, v3
	global_store_dwordx2 v[16:17], v[0:1], off offset:32 sc1
	s_cbranch_scc1 .LBB0_1137
